# attention K tile LDS swizzle uses 4 row bits (bit4 too): K fragment ds_read_b128 groups cover all 64 banks; K tile 1 re-staged before the loop
# speedup vs baseline: 1.0060x; 1.0030x over previous
; __device__ __forceinline__ int tidx() { int t = threadIdx.x; asm volatile("" : "+v"(t)); return t; }
; __device__ __forceinline__ void attn_dv256_body(const bf16* __restrict__ Qb, const bf16* __restrict__ Kh, const bf16* __restrict__ Vh,
;                                                 float* __restrict__ Ob, int seq, float kmax, char* lds) {
;     ...
;   const int tid = tidx(), wid = tid >> 6, lane = tid & 63, r32 = lane & 31, hi = lane >> 5;
;   const int rg = wid & 3, kh = wid >> 2;
;   char* V_lds = lds; char* K_lds = lds + 65536; char* XCH = lds + 98304; float* LI = (float*)(lds + 131072);
;   f32x16 o[4] = {}; bf16x8 qr[8];
;   const bf16* Qw = Qb + (long)(rg * 32 + r32) * LDQ + hi * 8;
; #pragma unroll
;   for (int d0 = 0; d0 < 8; ++d0) qr[d0] = St::ld8(Qw + d0 * 16);
;   float qq = 0.f;
; #pragma unroll
;   for (int d0 = 0; d0 < 8; ++d0)
; #pragma unroll
;     for (int e = 0; e < 8; ++e) { const float v = __uint_as_float(((unsigned)(unsigned short)qr[d0][e]) << 16); qq += v * v; }
;   qq += __shfl_xor(qq, 32);
;   constexpr float C = SCALE * 1.4426950408889634f;
;   const float mC = -sqrtf(qq) * kmax * C * 1.002f;
; __device__ __forceinline__ void attn_item(const u16* P, float* AO, const unsigned* kmaxu, int item, char* lds) {
;     int hm, qrow0, krow0, seq;
;     if (item < 512) { hm = item >> 6; qrow0 = (item & 63) * 128; krow0 = 0; seq = TT; }
;     else { hm = (item - 512) >> 1; qrow0 = TL + ((item - 512) & 1) * 128; krow0 = TL; seq = TC; }
;     const int h = hm >> 1;
;     const att::bf16* Pb = (const att::bf16*)P;
;     const att::bf16* Q = Pb + (size_t)qrow0 * PST + C_CQ + hm * 128;
;     const att::bf16* K = Pb + (size_t)krow0 * PST + C_CK + hm * 128;
;     const att::bf16* V = Pb + (size_t)krow0 * PST + C_CV + h * 256;
;     float* O = AO + (size_t)qrow0 * DM + hm * 256;
;     const float kmax = sqrtf(__uint_as_float(kmaxu[hm]));
;     att::attn_dv256_body(Q, K, V, O, seq, kmax, lds);
.LBB0_909:
	s_mul_i32 s7, s84, 0x4080
	s_mul_hi_u32 s1, s84, 0x4080
	s_add_u32 s7, s78, s7
	s_addc_u32 s1, s79, s1
	s_lshl_b32 s22, s34, 7
	s_ashr_i32 s23, s22, 31
	s_lshl_b64 s[38:39], s[22:23], 1
	s_add_u32 s42, s7, s38
	s_addc_u32 s43, s1, s39
	s_lshl_b32 s0, s0, 1
	s_add_u32 s7, s78, s0
	s_addc_u32 s13, s79, 0
	s_add_u32 s0, s7, s38
	s_addc_u32 s1, s13, s39
	s_add_u32 s38, s0, 0x2800
	s_addc_u32 s39, s1, 0
	s_and_b32 s0, s22, 0xffffff00
	s_ashr_i32 s1, s0, 31
	s_lshl_b64 s[0:1], s[0:1], 1
	s_add_u32 s0, s7, s0
	s_addc_u32 s1, s13, s1
	s_add_u32 s40, s0, 0x3000
	s_addc_u32 s41, s1, 0
	s_ashr_i32 s35, s34, 31
	s_lshl_b64 s[0:1], s[34:35], 2
	s_add_u32 s0, s20, s0
	s_addc_u32 s1, s21, s1
	v_mov_b32_e32 v3, v170
	global_load_dword v6, v165, s[0:1]
	s_mov_b64 s[0:1], 0x2000
	v_ashrrev_i32_e32 v2, 6, v3
	v_lshlrev_b32_e32 v0, 5, v2
	v_and_b32_e32 v186, 31, v3
	v_and_b32_e32 v185, 0x60, v0
	v_or_b32_e32 v0, v185, v186
	v_mul_u32_u24_e32 v0, 0x2040, v0
	v_bfe_u32 v184, v3, 5, 1
	v_lshlrev_b32_e32 v164, 1, v0
	v_lshl_add_u64 v[0:1], s[42:43], 0, v[164:165]
	v_lshlrev_b32_e32 v164, 4, v184
	v_lshl_add_u64 v[0:1], v[0:1], 0, v[164:165]
	v_add_co_u32_e32 v4, vcc, s95, v0
	s_mov_b32 s22, 0xf800000
	s_nop 0
	v_addc_co_u32_e32 v5, vcc, 0, v1, vcc
	global_load_dwordx4 v[80:83], v[4:5], off
	v_lshl_add_u64 v[0:1], v[0:1], 0, s[0:1]
	global_load_dwordx4 v[84:87], v[0:1], off offset:32
	global_load_dwordx4 v[88:91], v[0:1], off offset:64
	global_load_dwordx4 v[92:95], v[0:1], off offset:96
	global_load_dwordx4 v[96:99], v[0:1], off offset:128
	global_load_dwordx4 v[100:103], v[0:1], off offset:160
	global_load_dwordx4 v[104:107], v[0:1], off offset:192
	global_load_dwordx4 v[108:111], v[0:1], off offset:224
	v_ashrrev_i32_e32 v189, 4, v3
	v_add_u32_e32 v190, 32, v189
	s_movk_i32 s13, 0x2040
	s_cmp_lg_u32 0, -1
	v_ashrrev_i32_e32 v187, 8, v3
	v_and_b32_e32 v191, 63, v3
	v_lshlrev_b32_e32 v205, 4, v191
	v_mov_b32_e32 v132, 0
	v_mov_b32_e32 v144, 0
	v_mov_b32_e32 v192, 0
	s_mov_b32 s7, 0
	v_lshlrev_b32_e32 v209, 11, v2
	v_mov_b32_e32 v2, v192
	v_mov_b32_e32 v55, v192
	v_mov_b32_e32 v56, v192
	v_mov_b32_e32 v57, v192
	v_mov_b32_e32 v58, v192
	v_mov_b32_e32 v59, v192
	v_mov_b32_e32 v60, v192
	v_mov_b32_e32 v61, v192
	v_mov_b32_e32 v62, v192
	v_mov_b32_e32 v63, v192
	v_mov_b32_e32 v145, v144
	v_mov_b32_e32 v146, v144
	v_mov_b32_e32 v147, v144
	v_mov_b32_e32 v148, v144
	v_mov_b32_e32 v149, v144
	v_mov_b32_e32 v150, v144
	v_mov_b32_e32 v151, v144
	v_mov_b32_e32 v133, v132
	v_mov_b32_e32 v134, v132
	v_mov_b32_e32 v135, v132
	v_mov_b32_e32 v128, v132
	v_mov_b32_e32 v129, v132
	v_mov_b32_e32 v130, v132
	v_mov_b32_e32 v131, v132
	s_waitcnt vmcnt(8)
	v_mul_f32_e32 v4, 0x4f800000, v6
	v_cmp_gt_f32_e32 vcc, s22, v6
	s_waitcnt vmcnt(6)
	v_lshlrev_b32_e32 v14, 16, v84
	v_cndmask_b32_e32 v4, v6, v4, vcc
	v_sqrt_f32_e32 v7, v4
	v_lshlrev_b32_e32 v8, 16, v81
	v_and_b32_e32 v9, 0xffff0000, v81
	v_lshlrev_b32_e32 v10, 16, v82
	v_add_u32_e32 v0, -1, v7
	v_fma_f32 v1, -v0, v7, v4
	v_add_u32_e32 v5, 1, v7
	v_cmp_ge_f32_e64 s[0:1], 0, v1
	v_and_b32_e32 v1, 0xffff0000, v80
	v_fma_f32 v6, -v5, v7, v4
	v_cndmask_b32_e64 v7, v7, v0, s[0:1]
	v_lshlrev_b32_e32 v0, 16, v80
	v_mul_f32_e32 v54, v1, v1
	v_fmac_f32_e32 v54, v0, v0
	v_fmac_f32_e32 v54, v8, v8
	v_fmac_f32_e32 v54, v9, v9
	v_and_b32_e32 v11, 0xffff0000, v82
	v_fmac_f32_e32 v54, v10, v10
	v_lshlrev_b32_e32 v12, 16, v83
	v_fmac_f32_e32 v54, v11, v11
	v_and_b32_e32 v13, 0xffff0000, v83
	v_fmac_f32_e32 v54, v12, v12
	v_fmac_f32_e32 v54, v13, v13
	v_and_b32_e32 v15, 0xffff0000, v84
	v_fmac_f32_e32 v54, v14, v14
	v_lshlrev_b32_e32 v16, 16, v85
	v_fmac_f32_e32 v54, v15, v15
	v_and_b32_e32 v17, 0xffff0000, v85
	v_fmac_f32_e32 v54, v16, v16
	v_lshlrev_b32_e32 v18, 16, v86
	v_fmac_f32_e32 v54, v17, v17
	v_and_b32_e32 v19, 0xffff0000, v86
	v_fmac_f32_e32 v54, v18, v18
	v_lshlrev_b32_e32 v20, 16, v87
	v_fmac_f32_e32 v54, v19, v19
	v_and_b32_e32 v21, 0xffff0000, v87
	v_fmac_f32_e32 v54, v20, v20
	s_waitcnt vmcnt(5)
	v_lshlrev_b32_e32 v22, 16, v88
	v_fmac_f32_e32 v54, v21, v21
	v_and_b32_e32 v23, 0xffff0000, v88
	v_fmac_f32_e32 v54, v22, v22
	v_lshlrev_b32_e32 v24, 16, v89
	v_fmac_f32_e32 v54, v23, v23
	v_and_b32_e32 v25, 0xffff0000, v89
	v_fmac_f32_e32 v54, v24, v24
	v_lshlrev_b32_e32 v26, 16, v90
	v_fmac_f32_e32 v54, v25, v25
	v_and_b32_e32 v27, 0xffff0000, v90
	v_fmac_f32_e32 v54, v26, v26
	v_lshlrev_b32_e32 v28, 16, v91
	v_fmac_f32_e32 v54, v27, v27
	v_and_b32_e32 v29, 0xffff0000, v91
	v_fmac_f32_e32 v54, v28, v28
	s_waitcnt vmcnt(4)
	v_lshlrev_b32_e32 v30, 16, v92
	v_fmac_f32_e32 v54, v29, v29
	v_and_b32_e32 v31, 0xffff0000, v92
	v_fmac_f32_e32 v54, v30, v30
	v_lshlrev_b32_e32 v32, 16, v93
	v_fmac_f32_e32 v54, v31, v31
	v_and_b32_e32 v33, 0xffff0000, v93
	v_fmac_f32_e32 v54, v32, v32
	v_lshlrev_b32_e32 v34, 16, v94
	v_fmac_f32_e32 v54, v33, v33
	v_and_b32_e32 v35, 0xffff0000, v94
	v_fmac_f32_e32 v54, v34, v34
	v_lshlrev_b32_e32 v36, 16, v95
	v_fmac_f32_e32 v54, v35, v35
	v_and_b32_e32 v37, 0xffff0000, v95
	v_fmac_f32_e32 v54, v36, v36
	s_waitcnt vmcnt(3)
	v_lshlrev_b32_e32 v38, 16, v96
	v_fmac_f32_e32 v54, v37, v37
	v_and_b32_e32 v39, 0xffff0000, v96
	v_fmac_f32_e32 v54, v38, v38
	v_lshlrev_b32_e32 v40, 16, v97
	v_fmac_f32_e32 v54, v39, v39
	v_and_b32_e32 v41, 0xffff0000, v97
	v_fmac_f32_e32 v54, v40, v40
	v_lshlrev_b32_e32 v42, 16, v98
	v_fmac_f32_e32 v54, v41, v41
	v_and_b32_e32 v43, 0xffff0000, v98
	v_fmac_f32_e32 v54, v42, v42
	v_lshlrev_b32_e32 v44, 16, v99
	v_fmac_f32_e32 v54, v43, v43
	v_and_b32_e32 v45, 0xffff0000, v99
	v_fmac_f32_e32 v54, v44, v44
	s_waitcnt vmcnt(2)
; __device__ __forceinline__ int v_st(int k, int c) { const int kk = (k & ~0xC) | ((k & 4) << 1) | ((k & 8) >> 1); return ((kk >> 3) * 4 + (c >> 5)) * 512 + ((kk & 7) * 32 + (c & 31)) * 2; }
; __device__ __forceinline__ int v_rd_base(int lane) { return ((lane & 3) << 3) | (((lane >> 2) & 3) << 6) | (((lane >> 4) & 1) << 5) | (((lane >> 5) & 1) << 8); }
; #define KLOAD(k0) do { kr0 = St::ld8(&Kh[(long)((k0) + sr) * LDK + sc]); kr1 = St::ld8(&Kh[(long)((k0) + 32 + sr) * LDK + sc]); } while (0)
; #define VLOAD(k0) do { vr0 = St::ld8(&Vh[(long)((k0) + sr) * LDK + sc]); vr1 = St::ld8(&Vh[(long)((k0) + 32 + sr) * LDK + sc]); \
;     vr2 = St::ld8(&Vh[(long)((k0) + sr) * LDK + 128 + sc]); vr3 = St::ld8(&Vh[(long)((k0) + 32 + sr) * LDK + 128 + sc]); } while (0)
; #define KWRITE(b) do { *(bf16x8*)(K_lds + (b) * 16384 + KSWZ(sr, sc * 2)) = kr0; *(bf16x8*)(K_lds + (b) * 16384 + KSWZ(32 + sr, sc * 2)) = kr1; } while (0)
; #define VWRITE(b) do { *(bf16x8*)(V_lds + ((b) * 2) * 16384 + vst0) = vr0; *(bf16x8*)(V_lds + ((b) * 2) * 16384 + vst1) = vr1; \
;     *(bf16x8*)(V_lds + ((b) * 2 + 1) * 16384 + vst1) = vr2; *(bf16x8*)(V_lds + ((b) * 2 + 1) * 16384 + vst0) = vr3; } while (0)
; __device__ __forceinline__ void attn_dv256_body(const bf16* __restrict__ Qb, const bf16* __restrict__ Kh, const bf16* __restrict__ Vh,
;                                                 float* __restrict__ Ob, int seq, float kmax, char* lds) {
;     ...
;   const int sr = tid >> 4, sc = (tid & 15) * 8, vst0 = v_st(sr, sc), vst1 = v_st(32 + sr, sc);
;   const int vb0 = (int)(uintptr_t)V_lds + kh * 16384 + v_rd_base(lane);
;   bf16x8 kr0, kr1, vr0, vr1, vr2, vr3;
;     ...
;   const int NT = seq / KVBLK;
;   f32x16 pc, pn; pn = f32x16{};
;   bf16x8 q0 = {}, q1 = {}, q2 = {}, q3 = {};
;   char* XC0 = XCH;
;   KLOAD(0); VLOAD(0); asm volatile("s_waitcnt vmcnt(0)" ::: "memory"); KWRITE(0); VWRITE(0);
;   KLOAD(KVBLK); VLOAD(KVBLK); asm volatile("s_waitcnt vmcnt(0)" ::: "memory"); KWRITE(1); VWRITE(1);
;   __syncthreads();
	v_lshlrev_b32_e32 v46, 16, v100
	v_fmac_f32_e32 v54, v45, v45
	v_and_b32_e32 v47, 0xffff0000, v100
	v_fmac_f32_e32 v54, v46, v46
	v_lshlrev_b32_e32 v48, 16, v101
	v_fmac_f32_e32 v54, v47, v47
	v_and_b32_e32 v49, 0xffff0000, v101
	v_fmac_f32_e32 v54, v48, v48
	v_lshlrev_b32_e32 v50, 16, v102
	v_fmac_f32_e32 v54, v49, v49
	v_lshlrev_b32_e32 v49, 3, v3
	v_and_b32_e32 v51, 0xffff0000, v102
	v_fmac_f32_e32 v54, v50, v50
	v_and_b32_e32 v32, 0x78, v49
	v_mov_b32_e32 v33, v165
	v_lshlrev_b32_e32 v52, 16, v103
	v_fmac_f32_e32 v54, v51, v51
	v_mad_i64_i32 v[8:9], s[0:1], v189, s13, v[32:33]
	v_mad_i64_i32 v[10:11], s[0:1], v190, s13, v[32:33]
	v_and_b32_e32 v53, 0xffff0000, v103
	v_fmac_f32_e32 v54, v52, v52
	v_lshlrev_b64 v[16:17], 1, v[8:9]
	v_lshlrev_b64 v[18:19], 1, v[10:11]
	v_fmac_f32_e32 v54, v53, v53
	s_waitcnt vmcnt(1)
	v_lshlrev_b32_e32 v0, 16, v104
	v_lshl_add_u64 v[8:9], s[38:39], 0, v[16:17]
	v_lshl_add_u64 v[12:13], s[38:39], 0, v[18:19]
	v_fmac_f32_e32 v54, v0, v0
	v_and_b32_e32 v0, 0xffff0000, v104
	v_mad_i64_i32 v[24:25], s[0:1], v189, s13, 0
	v_mad_i64_i32 v[26:27], s[0:1], v190, s13, 0
	global_load_dwordx4 v[8:11], v[8:9], off
	s_nop 0
	global_load_dwordx4 v[12:15], v[12:13], off
	v_add_u32_e32 v34, 64, v189
	v_add_u32_e32 v36, 0x60, v189
	v_fmac_f32_e32 v54, v0, v0
	v_lshlrev_b32_e32 v0, 1, v32
	v_lshl_add_u64 v[24:25], v[24:25], 1, s[40:41]
	v_mov_b32_e32 v1, v165
	v_lshl_add_u64 v[26:27], v[26:27], 1, s[40:41]
	v_mad_i64_i32 v[40:41], s[0:1], v34, s13, 0
	v_mad_i64_i32 v[34:35], s[0:1], v34, s13, v[32:33]
	v_mad_i64_i32 v[32:33], s[0:1], v36, s13, v[32:33]
	v_lshl_add_u64 v[16:17], s[40:41], 0, v[16:17]
	v_lshl_add_u64 v[20:21], s[40:41], 0, v[18:19]
	v_lshl_add_u64 v[24:25], v[24:25], 0, v[0:1]
	v_lshl_add_u64 v[28:29], v[26:27], 0, v[0:1]
	v_lshlrev_b64 v[42:43], 1, v[34:35]
	v_lshlrev_b64 v[46:47], 1, v[32:33]
	global_load_dwordx4 v[16:19], v[16:17], off
	s_nop 0
	global_load_dwordx4 v[20:23], v[20:21], off
	s_nop 0
	global_load_dwordx4 v[24:27], v[24:25], off offset:256
	s_nop 0
	global_load_dwordx4 v[28:31], v[28:29], off offset:256
	s_waitcnt vmcnt(0)
	v_lshl_add_u64 v[34:35], s[38:39], 0, v[42:43]
	v_mad_i64_i32 v[44:45], s[0:1], v36, s13, 0
	v_lshl_add_u64 v[36:37], s[38:39], 0, v[46:47]
	v_lshl_add_u64 v[42:43], s[40:41], 0, v[42:43]
	v_lshl_add_u64 v[40:41], v[40:41], 1, s[40:41]
	global_load_dwordx4 v[32:35], v[34:35], off
	s_nop 0
	global_load_dwordx4 v[36:39], v[36:37], off
	v_lshl_add_u64 v[46:47], s[40:41], 0, v[46:47]
	global_load_dwordx4 v[116:119], v[42:43], off
	global_load_dwordx4 v[112:115], v[46:47], off
	v_lshl_add_u64 v[40:41], v[40:41], 0, v[0:1]
	v_lshl_add_u64 v[42:43], v[44:45], 1, s[40:41]
	v_lshl_add_u64 v[42:43], v[42:43], 0, v[0:1]
	global_load_dwordx4 v[120:123], v[40:41], off offset:256
	global_load_dwordx4 v[124:127], v[42:43], off offset:256
	v_lshlrev_b32_e32 v48, 16, v105
	v_fmac_f32_e32 v54, v48, v48
	v_and_b32_e32 v40, 0xffff0000, v105
	v_fmac_f32_e32 v54, v40, v40
	v_lshlrev_b32_e32 v40, 16, v106
	v_fmac_f32_e32 v54, v40, v40
	v_and_b32_e32 v40, 0xffff0000, v106
	v_fmac_f32_e32 v54, v40, v40
	v_lshlrev_b32_e32 v40, 16, v107
	v_fmac_f32_e32 v54, v40, v40
	v_and_b32_e32 v40, 0xffff0000, v107
	v_and_b32_e32 v41, 0xfffff0, v189
	v_lshlrev_b32_e32 v42, 1, v189
	v_fmac_f32_e32 v54, v40, v40
	s_waitcnt vmcnt(12)
	v_lshlrev_b32_e32 v40, 16, v108
	v_and_or_b32 v41, v42, 8, v41
	v_fmac_f32_e32 v54, v40, v40
	v_and_b32_e32 v40, 0xffff0000, v108
	v_lshrrev_b32_e32 v42, 1, v189
	v_lshrrev_b32_e32 v41, 1, v41
	v_bfe_u32 v43, v49, 5, 2
	v_and_b32_e32 v44, 3, v189
	v_fmac_f32_e32 v54, v40, v40
	v_lshlrev_b32_e32 v40, 16, v109
	v_or_b32_e32 v41, v41, v43
	v_and_or_b32 v42, v42, 4, v44
	v_fmac_f32_e32 v54, v40, v40
	v_and_b32_e32 v40, 0xffff0000, v109
	v_lshlrev_b32_e32 v41, 9, v41
	v_lshlrev_b32_e32 v42, 6, v42
	v_and_b32_e32 v44, 48, v0
	v_fmac_f32_e32 v54, v40, v40
	v_lshlrev_b32_e32 v40, 16, v110
	v_or3_b32 v193, v41, v42, v44
	v_and_b32_e32 v41, 0xfffff0, v190
	v_lshlrev_b32_e32 v45, 1, v190
	v_fmac_f32_e32 v54, v40, v40
	v_and_b32_e32 v40, 0xffff0000, v110
	v_and_or_b32 v41, v45, 8, v41
	v_fmac_f32_e32 v54, v40, v40
	v_lshlrev_b32_e32 v40, 16, v111
	v_lshrrev_b32_e32 v41, 1, v41
	v_fmac_f32_e32 v54, v40, v40
	v_and_b32_e32 v40, 0xffff0000, v111
	v_or_b32_e32 v41, v41, v43
	v_fmac_f32_e32 v54, v40, v40
	v_xor_b32_e32 v40, 32, v171
	v_lshlrev_b32_e32 v41, 9, v41
	v_cmp_lt_i32_e64 s[0:1], v40, v172
	v_or3_b32 v194, v41, v42, v44
	v_lshlrev_b32_e32 v41, 8, v189
	v_and_b32_e32 v42, 0x70, v3
	v_cndmask_b32_e64 v40, v171, v40, s[0:1]
	s_cselect_b32 s13, 0, 0
	v_bitop3_b32 v195, v0, v41, v42 bitop3:0xde
	s_add_i32 s0, 0, 0x10000
	v_add_u32_e32 v41, s0, v195
	s_waitcnt vmcnt(11)
	ds_write_b128 v41, v[8:11]
	v_lshlrev_b32_e32 v8, 8, v190
	v_bitop3_b32 v196, v0, v8, v42 bitop3:0xde
	v_add_u32_e32 v8, s0, v196
	s_waitcnt vmcnt(10)
	ds_write_b128 v8, v[12:15]
	v_add_u32_e32 v8, 0, v193
	v_add_u32_e32 v9, 0, v194
	s_add_i32 s1, 0, 0x14000
	s_waitcnt vmcnt(9)
	ds_write_b128 v8, v[16:19]
	s_waitcnt vmcnt(8)
	ds_write_b128 v9, v[20:23]
	s_waitcnt vmcnt(7)
	ds_write_b128 v9, v[24:27] offset:16384
	s_waitcnt vmcnt(6)
	ds_write_b128 v8, v[28:31] offset:16384
	v_add_u32_e32 v10, s1, v195
	s_waitcnt vmcnt(0)
	v_lshlrev_b32_e32 v12, 4, v3
	v_and_b32_e32 v16, 0x70, v12
	v_bitop3_b32 v199, v164, v16, 32 bitop3:0x36
	s_waitcnt vmcnt(5)
	ds_write_b128 v10, v[32:35]
	v_add_u32_e32 v10, s1, v196
	s_waitcnt vmcnt(4)
	ds_write_b128 v10, v[36:39]
	s_waitcnt vmcnt(3)
	ds_write_b128 v8, v[116:119] offset:32768
	s_waitcnt vmcnt(2)
	ds_write_b128 v9, v[112:115] offset:32768
	s_waitcnt vmcnt(1)
	ds_write_b128 v9, v[120:123] offset:49152
	s_waitcnt vmcnt(0)
	ds_write_b128 v8, v[124:127] offset:49152
	v_lshlrev_b32_e32 v8, 13, v187
	v_lshlrev_b32_e32 v9, 8, v186
	v_add3_u32 v197, s0, v8, v9
	s_movk_i32 s0, 0x70
	v_bitop3_b32 v198, v164, v12, s0 bitop3:0x78
	v_add_u32_e32 v8, v197, v198
	s_waitcnt lgkmcnt(0)
	s_barrier
; #define KLOAD(k0) do { kr0 = St::ld8(&Kh[(long)((k0) + sr) * LDK + sc]); kr1 = St::ld8(&Kh[(long)((k0) + 32 + sr) * LDK + sc]); } while (0)
; #define QKH(P, b) do { P = f32x16{}; _Pragma("unroll") for (int d0 = 0; d0 < 8; ++d0) { const int cb = (d0 * 16 + hi * 8) * 2; \
;     const bf16x8 kf = *reinterpret_cast<const bf16x8*>(K_lds + (b) * 16384 + KSWZ(32 * kh + r32, cb)); P = __builtin_amdgcn_mfma_f32_32x32x16_bf16(kf, qr[d0], P, 0, 0, 0); } } while (0)
; __device__ __forceinline__ void attn_dv256_body(const bf16* __restrict__ Qb, const bf16* __restrict__ Kh, const bf16* __restrict__ Vh,
;                                                 float* __restrict__ Ob, int seq, float kmax, char* lds) {
;     ...
;   QKH(pc, 0);
;   KLOAD((2 < NT ? 2 : NT - 1) * KVBLK);
;   __syncthreads();
	ds_read_b128 v[8:11], v8
	v_cmp_lt_f32_e64 s[0:1], 0, v6
	v_lshlrev_b32_e32 v188, 2, v40
	ds_bpermute_b32 v40, v188, v54
	v_cndmask_b32_e64 v5, v7, v5, s[0:1]
	v_add_u32_e32 v7, v197, v199
	ds_read_b128 v[12:15], v7
	s_waitcnt lgkmcnt(2)
	v_mfma_f32_32x32x16_bf16 v[64:79], v[8:11], v[80:83], 0
	v_mul_f32_e32 v6, 0x37800000, v5
	v_cndmask_b32_e32 v5, v5, v6, vcc
	s_waitcnt lgkmcnt(1)
	v_add_f32_e32 v6, v54, v40
	v_mul_f32_e32 v7, 0x4f800000, v6
	v_cmp_gt_f32_e32 vcc, s22, v6
	v_bitop3_b32 v200, v164, v16, 64 bitop3:0x36
	v_lshlrev_b32_e32 v3, 1, v3
	v_cndmask_b32_e32 v17, v6, v7, vcc
	v_add_u32_e32 v6, v197, v200
	ds_read_b128 v[6:9], v6
	s_waitcnt lgkmcnt(1)
	v_mfma_f32_32x32x16_bf16 v[64:79], v[12:15], v[84:87], v[64:79]
	v_mov_b32_e32 v15, 0x260
	v_cmp_class_f32_e64 s[0:1], v4, v15
	v_sqrt_f32_e32 v18, v17
	v_and_b32_e32 v3, 32, v3
	v_cndmask_b32_e64 v14, v5, v4, s[0:1]
	s_movk_i32 s0, 0x60
	v_bitop3_b32 v201, v164, v16, s0 bitop3:0x36
	v_add_u32_e32 v5, v197, v201
	ds_read_b128 v[10:13], v5
	s_waitcnt lgkmcnt(1)
	v_mfma_f32_32x32x16_bf16 v[64:79], v[6:9], v[88:91], v[64:79]
	v_add_u32_e32 v4, -1, v18
	v_fma_f32 v5, -v4, v18, v17
	v_cmp_ge_f32_e64 s[0:1], 0, v5
	v_add_u32_e32 v9, 1, v18
	v_lshl_add_u64 v[166:167], s[38:39], 0, v[0:1]
	v_cndmask_b32_e64 v8, v18, v4, s[0:1]
	s_movk_i32 s0, 0x80
	v_bitop3_b32 v202, v164, v16, s0 bitop3:0x36
	v_add_u32_e32 v4, v197, v202
	ds_read_b128 v[4:7], v4
	s_waitcnt lgkmcnt(1)
	v_mfma_f32_32x32x16_bf16 v[64:79], v[10:13], v[92:95], v[64:79]
	v_fma_f32 v10, -v9, v18, v17
	v_cmp_lt_f32_e64 s[0:1], 0, v10
	v_lshl_add_u64 v[168:169], s[40:41], 0, v[0:1]
	v_mov_b32_e32 v18, v192
	v_cndmask_b32_e64 v12, v8, v9, s[0:1]
	s_movk_i32 s0, 0xa0
	v_bitop3_b32 v203, v164, v16, s0 bitop3:0x36
	v_add_u32_e32 v8, v197, v203
	ds_read_b128 v[8:11], v8
	s_waitcnt lgkmcnt(1)
	v_mfma_f32_32x32x16_bf16 v[64:79], v[4:7], v[96:99], v[64:79]
	v_mul_f32_e32 v13, 0x37800000, v12
	v_cndmask_b32_e32 v4, v12, v13, vcc
	v_cmp_class_f32_e32 vcc, v17, v15
	s_movk_i32 s0, 0xc0
	v_bitop3_b32 v204, v164, v16, s0 bitop3:0x36
	v_cndmask_b32_e32 v4, v4, v17, vcc
	v_mul_f32_e32 v12, v14, v4
	v_add_u32_e32 v4, v197, v204
	ds_read_b128 v[4:7], v4
	s_waitcnt lgkmcnt(1)
	v_mfma_f32_32x32x16_bf16 v[64:79], v[8:11], v[100:103], v[64:79]
	s_movk_i32 s0, 0xe0
	v_bitop3_b32 v206, v164, v16, s0 bitop3:0x36
	v_add_u32_e32 v8, v197, v206
	v_lshlrev_b32_e32 v14, 3, v191
	ds_read_b128 v[8:11], v8
	v_lshlrev_b32_e32 v13, 14, v187
	v_mul_f32_e32 v12, 0x3e0293ee, v12
	s_waitcnt lgkmcnt(1)
	v_mfma_f32_32x32x16_bf16 v[64:79], v[4:7], v[104:107], v[64:79]
	v_and_b32_e32 v4, 0xc0, v205
	v_and_or_b32 v4, v14, 24, v4
	v_and_b32_e32 v5, 0x100, v14
	v_or3_b32 v3, v4, v3, v5
	v_add3_u32 v207, v13, s13, v3
	v_add_u32_e32 v3, 0x80, v189
	v_mov_b64_e32 v[4:5], s[38:39]
	v_mad_i64_i32 v[6:7], s[22:23], v3, s93, v[4:5]
	v_add_u32_e32 v3, 0xa0, v189
	v_lshl_add_u64 v[6:7], v[6:7], 0, v[0:1]
	v_mad_i64_i32 v[4:5], s[22:23], v3, s93, v[4:5]
	v_lshl_add_u64 v[4:5], v[4:5], 0, v[0:1]
	global_load_dwordx4 v[136:139], v[6:7], off
	global_load_dwordx4 v[140:143], v[4:5], off
	s_waitcnt lgkmcnt(0)
	v_mfma_f32_32x32x16_bf16 v[64:79], v[8:11], v[108:111], v[64:79]
	v_mul_f32_e32 v208, 0xbf804189, v12
	s_add_i32 s0, s6, -1
	v_mov_b32_e32 v0, 0
	v_mov_b32_e32 v1, v192
	v_mov_b32_e32 v3, v192
	v_mov_b32_e32 v4, v192
	v_mov_b32_e32 v5, v192
	v_mov_b32_e32 v6, v192
	v_mov_b32_e32 v7, v192
	v_mov_b32_e32 v8, v192
	v_mov_b32_e32 v9, v192
	v_mov_b32_e32 v10, v192
	v_mov_b32_e32 v11, v192
	v_mov_b32_e32 v12, v192
	v_mov_b32_e32 v13, v192
	v_mov_b32_e32 v14, v192
	v_mov_b32_e32 v15, v192
	v_mov_b32_e32 v16, 0
	v_mov_b32_e32 v17, v192
	v_mov_b32_e32 v19, v192
	v_mov_b32_e32 v20, v192
	v_mov_b32_e32 v21, v192
	v_mov_b32_e32 v22, v192
	v_mov_b32_e32 v23, v192
	v_mov_b32_e32 v24, v192
	v_mov_b32_e32 v25, v192
	v_mov_b32_e32 v26, v192
	v_mov_b32_e32 v27, v192
	v_mov_b32_e32 v28, v192
	v_mov_b32_e32 v29, v192
	v_mov_b32_e32 v30, v192
	v_mov_b32_e32 v31, v192
	v_mov_b32_e32 v32, 0
	v_mov_b32_e32 v33, v192
	v_mov_b32_e32 v34, v192
	v_mov_b32_e32 v35, v192
	v_mov_b32_e32 v36, v192
	v_mov_b32_e32 v37, v192
	v_mov_b32_e32 v38, v192
	v_mov_b32_e32 v39, v192
	v_mov_b32_e32 v40, v192
	v_mov_b32_e32 v41, v192
	v_mov_b32_e32 v42, v192
	v_mov_b32_e32 v43, v192
	v_mov_b32_e32 v44, v192
	v_mov_b32_e32 v45, v192
	v_mov_b32_e32 v46, v192
	v_mov_b32_e32 v47, v192
	v_mov_b32_e32 v48, 0
	v_mov_b32_e32 v49, v192
	v_mov_b32_e32 v50, v192
	v_mov_b32_e32 v51, v192
	v_mov_b32_e32 v52, v192
	v_mov_b32_e32 v53, v192
	v_mov_b32_e32 v54, v192
	s_barrier
	v_bfe_u32 v218, v170, 4, 1
	v_lshlrev_b32_e32 v218, 7, v218
	v_xor_b32_e32 v198, v198, v218
	v_xor_b32_e32 v199, v199, v218
	v_xor_b32_e32 v200, v200, v218
	v_xor_b32_e32 v201, v201, v218
	v_xor_b32_e32 v202, v202, v218
	v_xor_b32_e32 v203, v203, v218
	v_xor_b32_e32 v204, v204, v218
	v_xor_b32_e32 v206, v206, v218
	v_bfe_u32 v218, v170, 8, 1
	v_lshlrev_b32_e32 v218, 7, v218
	v_xor_b32_e32 v195, v195, v218
	v_xor_b32_e32 v196, v196, v218
	v_add_u32_e32 v218, 64, v189
	v_add_u32_e32 v220, 64, v190
	v_mad_i64_i32 v[218:219], s[22:23], v218, s93, v[166:167]
	v_mad_i64_i32 v[220:221], s[22:23], v220, s93, v[166:167]
	global_load_dwordx4 v[210:213], v[218:219], off
	global_load_dwordx4 v[214:217], v[220:221], off
	s_waitcnt vmcnt(0)
	v_add_u32_e32 v218, 0x14000, v195
	v_add_u32_e32 v219, 0x14000, v196
	ds_write_b128 v218, v[210:213]
	ds_write_b128 v219, v[214:217]
	s_waitcnt lgkmcnt(0)
	s_barrier
